# diff-attention combine loop: three of the four gain-vector loads issued with the row loads ahead of the first wait (prologue de-serialisation)
# baseline (speedup 1.0000x reference)
; __device__ __forceinline__ float bf2f(bf16_t v) { return __uint_as_float((unsigned)v << 16); }
; __device__ __forceinline__ u32x4 pack8(const float* v) { u32x4 w; w.x = cvt_pk_bf16(v[0], v[1]); w.y = cvt_pk_bf16(v[2], v[3]); w.z = cvt_pk_bf16(v[4], v[5]); w.w = cvt_pk_bf16(v[6], v[7]); return w; }
; __global__ void __launch_bounds__(512) mk_fwd(Params P) {
;     ...
;             for (int row = gw; row < M; row += NGW) {
;                 const bf16_t* p0 = Ob + (size_t)(hh >> 2) * ((size_t)M * 1024) + (size_t)row * 1024 + ((2 * hh) & 7) * 128 + v0; const bf16_t* p1 = p0 + 128;
;                 const bf16x8 a0 = __builtin_nontemporal_load((const bf16x8*)p0), a1 = __builtin_nontemporal_load((const bf16x8*)(p0 + 8)), b0 = __builtin_nontemporal_load((const bf16x8*)p1), b1 = __builtin_nontemporal_load((const bf16x8*)(p1 + 8));
;                 float o[16]; float s = 0.f;
; #pragma unroll
;                 for (int e = 0; e < 8; ++e) { o[e] = bf2f((bf16_t)a0[e]) - lam_full * bf2f((bf16_t)b0[e]); o[8 + e] = bf2f((bf16_t)a1[e]) - lam_full * bf2f((bf16_t)b1[e]); }
; #pragma unroll
;                 for (int e = 0; e < 16; ++e) s += o[e] * o[e];
;                 s += __shfl_xor(s, 1); s += __shfl_xor(s, 2); s += __shfl_xor(s, 4);
;                 const float rinv = rsqrtf(s * (1.f / 128.f) + EPS) * 0.8f;
; #pragma unroll
;                 for (int e = 0; e < 16; ++e) o[e] = o[e] * rinv * P.in[13][v0 + e];
;                 bf16_t* dp = A2b + (size_t)row * 1024 + hh * 128 + v0;
;                 *(u32x4*)dp = pack8(o); *(u32x4*)(dp + 8) = pack8(o + 8);
;             }
.LBB0_80:
	s_nop 0
	v_lshl_add_u64 v[8:9], v[6:7], 0, v[144:145]
	v_add_co_u32_e32 v20, vcc, 0x12569000, v8
	s_add_i32 s3, s3, s42
	s_nop 0
	v_addc_co_u32_e32 v21, vcc, 0, v9, vcc
	flat_load_dwordx4 v[8:11], v[20:21] nt
	flat_load_dwordx4 v[12:15], v[20:21] offset:16 nt
	flat_load_dwordx4 v[16:19], v[20:21] offset:256 nt
	s_nop 0
	flat_load_dwordx4 v[20:23], v[20:21] offset:272 nt
	global_load_dwordx4 v[32:35], v[2:3], off offset:32
	global_load_dwordx4 v[36:39], v[2:3], off offset:16
	global_load_dwordx4 v[40:43], v[2:3], off
	v_lshl_add_u64 v[6:7], v[6:7], 0, s[6:7]
	s_cmpk_gt_i32 s3, 0x43ff
	s_waitcnt vmcnt(0) lgkmcnt(0)
	v_and_b32_e32 v57, 0xffff0000, v9
	v_and_b32_e32 v29, 0xffff0000, v15
	v_lshlrev_b32_e32 v28, 16, v15
	v_and_b32_e32 v31, 0xffff0000, v23
	v_lshlrev_b32_e32 v30, 16, v23
	v_pk_fma_f32 v[44:45], v[0:1], v[30:31], v[28:29] neg_lo:[1,0,0] neg_hi:[1,0,0]
	global_load_dwordx4 v[28:31], v[2:3], off offset:48
	v_lshlrev_b32_e32 v56, 16, v9
	v_and_b32_e32 v59, 0xffff0000, v17
	v_lshlrev_b32_e32 v58, 16, v17
	v_and_b32_e32 v9, 0xffff0000, v8
	v_lshlrev_b32_e32 v8, 16, v8
	v_and_b32_e32 v17, 0xffff0000, v16
	v_lshlrev_b32_e32 v16, 16, v16
	v_pk_fma_f32 v[8:9], v[0:1], v[16:17], v[8:9] neg_lo:[1,0,0] neg_hi:[1,0,0]
	v_and_b32_e32 v49, 0xffff0000, v13
	v_lshlrev_b32_e32 v48, 16, v13
	v_and_b32_e32 v51, 0xffff0000, v21
	v_lshlrev_b32_e32 v50, 16, v21
	v_and_b32_e32 v13, 0xffff0000, v12
	v_lshlrev_b32_e32 v12, 16, v12
	v_and_b32_e32 v21, 0xffff0000, v20
	v_lshlrev_b32_e32 v20, 16, v20
	v_pk_fma_f32 v[56:57], v[0:1], v[58:59], v[56:57] neg_lo:[1,0,0] neg_hi:[1,0,0]
	v_pk_mul_f32 v[16:17], v[8:9], v[8:9]
	v_pk_fma_f32 v[52:53], v[0:1], v[20:21], v[12:13] neg_lo:[1,0,0] neg_hi:[1,0,0]
	v_and_b32_e32 v21, 0xffff0000, v11
	v_lshlrev_b32_e32 v20, 16, v11
	v_and_b32_e32 v55, 0xffff0000, v19
	v_lshlrev_b32_e32 v54, 16, v19
	v_and_b32_e32 v11, 0xffff0000, v10
	v_lshlrev_b32_e32 v10, 16, v10
	v_and_b32_e32 v19, 0xffff0000, v18
	v_lshlrev_b32_e32 v18, 16, v18
	v_pk_mul_f32 v[58:59], v[56:57], v[56:57]
	v_add_f32_e32 v16, v16, v17
	v_pk_fma_f32 v[10:11], v[0:1], v[18:19], v[10:11] neg_lo:[1,0,0] neg_hi:[1,0,0]
	v_add_f32_e32 v16, v16, v58
	v_pk_mul_f32 v[18:19], v[10:11], v[10:11]
	v_add_f32_e32 v16, v16, v59
	v_pk_fma_f32 v[20:21], v[0:1], v[54:55], v[20:21] neg_lo:[1,0,0] neg_hi:[1,0,0]
	v_add_f32_e32 v16, v16, v18
	v_pk_mul_f32 v[54:55], v[20:21], v[20:21]
	v_add_f32_e32 v16, v16, v19
	v_add_f32_e32 v16, v16, v54
	v_pk_mul_f32 v[12:13], v[52:53], v[52:53]
	v_add_f32_e32 v16, v16, v55
	v_pk_fma_f32 v[48:49], v[0:1], v[50:51], v[48:49] neg_lo:[1,0,0] neg_hi:[1,0,0]
	v_add_f32_e32 v12, v16, v12
	v_and_b32_e32 v15, 0xffff0000, v14
	v_lshlrev_b32_e32 v14, 16, v14
	v_and_b32_e32 v23, 0xffff0000, v22
	v_lshlrev_b32_e32 v22, 16, v22
	v_pk_mul_f32 v[50:51], v[48:49], v[48:49]
	v_add_f32_e32 v12, v12, v13
	v_pk_fma_f32 v[22:23], v[0:1], v[22:23], v[14:15] neg_lo:[1,0,0] neg_hi:[1,0,0]
	v_add_f32_e32 v12, v12, v50
	v_pk_mul_f32 v[14:15], v[22:23], v[22:23]
	v_add_f32_e32 v12, v12, v51
	v_add_f32_e32 v12, v12, v14
	v_pk_mul_f32 v[46:47], v[44:45], v[44:45]
	v_add_f32_e32 v12, v12, v15
	v_add_f32_e32 v12, v12, v46
	v_add_f32_e32 v12, v12, v47
	ds_bpermute_b32 v13, v24, v12
	s_waitcnt lgkmcnt(0)
	v_add_f32_e32 v12, v12, v13
	ds_bpermute_b32 v13, v25, v12
	s_waitcnt lgkmcnt(0)
	v_add_f32_e32 v12, v12, v13
	ds_bpermute_b32 v13, v26, v12
	s_waitcnt lgkmcnt(0)
	v_add_f32_e32 v12, v12, v13
	v_fmamk_f32 v12, v12, 0x3c000000, v186
	v_cmp_gt_f32_e32 vcc, s53, v12
	v_mul_f32_e32 v13, 0x4b800000, v12
	s_nop 0
	v_cndmask_b32_e32 v12, v12, v13, vcc
	v_rsq_f32_e32 v12, v12
	s_nop 0
	v_mul_f32_e32 v13, 0x45800000, v12
	v_cndmask_b32_e32 v12, v12, v13, vcc
	v_mul_f32_e32 v46, 0x3f4ccccd, v12
	v_pk_mul_f32 v[10:11], v[46:47], v[10:11] op_sel_hi:[0,1]
	s_waitcnt vmcnt(1)
	v_pk_mul_f32 v[16:17], v[10:11], v[36:37]
	v_pk_mul_f32 v[10:11], v[46:47], v[20:21] op_sel_hi:[0,1]
	v_pk_mul_f32 v[12:13], v[46:47], v[56:57] op_sel_hi:[0,1]
	v_pk_mul_f32 v[20:21], v[10:11], v[38:39]
	v_pk_mul_f32 v[10:11], v[46:47], v[52:53] op_sel_hi:[0,1]
	v_pk_mul_f32 v[8:9], v[46:47], v[8:9] op_sel_hi:[0,1]
	s_waitcnt vmcnt(0)
	v_pk_mul_f32 v[12:13], v[12:13], v[42:43]
	v_pk_mul_f32 v[10:11], v[10:11], v[32:33]
	v_pk_mul_f32 v[14:15], v[46:47], v[48:49] op_sel_hi:[0,1]
	v_pk_mul_f32 v[18:19], v[46:47], v[22:23] op_sel_hi:[0,1]
	v_pk_mul_f32 v[22:23], v[46:47], v[44:45] op_sel_hi:[0,1]
	v_lshl_add_u64 v[32:33], v[4:5], 0, v[144:145]
	v_pk_mul_f32 v[8:9], v[8:9], v[40:41]
	v_pk_mul_f32 v[14:15], v[14:15], v[34:35]
	v_pk_mul_f32 v[18:19], v[18:19], v[28:29]
	v_pk_mul_f32 v[22:23], v[22:23], v[30:31]
	v_cvt_pk_bf16_f32 v29, v12, v13
	v_add_co_u32_e32 v12, vcc, s47, v32
	v_cvt_pk_bf16_f32 v28, v8, v9
	v_cvt_pk_bf16_f32 v30, v16, v17
	v_cvt_pk_bf16_f32 v31, v20, v21
	v_addc_co_u32_e32 v13, vcc, 0, v33, vcc
	v_cvt_pk_bf16_f32 v8, v10, v11
	v_cvt_pk_bf16_f32 v9, v14, v15
	v_cvt_pk_bf16_f32 v10, v18, v19
	v_cvt_pk_bf16_f32 v11, v22, v23
	v_lshl_add_u64 v[4:5], v[4:5], 0, s[6:7]
	flat_store_dwordx4 v[12:13], v[28:31]
	flat_store_dwordx4 v[12:13], v[8:11] offset:16
	s_cbranch_scc0 .LBB0_80
